# LN f32 and prep weight dwordx4 stores also write-through (sc1)
# baseline (speedup 1.0000x reference)
; DI void phase_ln(const P& p, int l) {
;     ...
;   for (int row = r0; row < r1; row += 2) {
;     const bool two = row + 1 < r1;
;     const int rowb = two ? row + 1 : row;
;     float4 v[2][4];
; #pragma unroll
;     for (int i = 0; i < 4; ++i) {
;       v[0][i] = *(const float4*)(Zb + (size_t)row * 1024 + i * 256 + lane * 4);
;       v[1][i] = *(const float4*)(Zb + (size_t)rowb * 1024 + i * 256 + lane * 4);
;     }
; #pragma unroll
;     for (int h = 0; h < 2; ++h) {
;       if (h && !two) break;
;       const int rr = h ? rowb : row;
;       float s = 0.f;
; #pragma unroll
;       for (int i = 0; i < 4; ++i) s += (v[h][i].x + v[h][i].y) + (v[h][i].z + v[h][i].w);
; #pragma unroll
;       for (int o = 32; o >= 1; o >>= 1) s += __shfl_xor(s, o);
;       const float mean = s * (1.f / 1024.f);
;       float q = 0.f;
; #pragma unroll
;       for (int i = 0; i < 4; ++i) {
;         v[h][i].x -= mean; v[h][i].y -= mean; v[h][i].z -= mean; v[h][i].w -= mean;
;         q += (v[h][i].x * v[h][i].x + v[h][i].y * v[h][i].y) + (v[h][i].z * v[h][i].z + v[h][i].w * v[h][i].w);
;       }
; #pragma unroll
;       for (int o = 32; o >= 1; o >>= 1) q += __shfl_xor(q, o);
;       const float rstd = rsqrtf(q * (1.f / 1024.f) + 1e-5f);
;       const int mr = rr < MLAT ? (rr >> 11) : 16;
;       const float* md = p.mod + (size_t)(1 * 17 + mr) * 3072;
; #pragma unroll
;       for (int i = 0; i < 4; ++i) {
;         const int col = i * 256 + lane * 4;
;         float4 y;
;         y.x = v[h][i].x * rstd * g4[i].x + b4[i].x;
;         y.y = v[h][i].y * rstd * g4[i].y + b4[i].y;
;         y.z = v[h][i].z * rstd * g4[i].z + b4[i].z;
;         y.w = v[h][i].w * rstd * g4[i].w + b4[i].w;
;         if (l == 1 || rr < MLAT) *(float4*)(p.out + (size_t)rr * 1024 + col) = y;
.Lln_nopf:
	v_add_u32_e32 v63, 1, v62
	v_cmp_lt_i32_e64 s[40:41], v63, v65
	v_lshl_add_u64 v[90:91], v[80:81], 0, v[78:79]
	v_cmp_gt_i32_e32 vcc, s21, v62
	v_cndmask_b32_e64 v86, v62, v63, s[40:41]
	v_ashrrev_i32_e32 v87, 31, v86
	v_lshlrev_b64 v[88:89], 12, v[86:87]
	v_lshl_add_u64 v[38:39], v[66:67], 0, v[88:89]
	global_load_dwordx4 v[34:37], v[38:39], off
	global_load_dwordx4 v[46:49], v[38:39], off offset:1024
	global_load_dwordx4 v[42:45], v[38:39], off offset:2048
	s_nop 0
	global_load_dwordx4 v[38:41], v[38:39], off offset:3072
	s_nop 0
	global_load_dwordx4 v[50:53], v[90:91], off offset:3072
	global_load_dwordx4 v[54:57], v[90:91], off offset:2048
	global_load_dwordx4 v[58:61], v[90:91], off offset:1024
	s_or_b64 s[52:53], s[46:47], vcc
	s_waitcnt vmcnt(1)
	v_mov_b32_e32 v0, v57
	s_waitcnt vmcnt(0)
	v_mov_b32_e32 v92, v58
	v_mov_b32_e32 v93, v60
	v_mov_b32_e32 v98, v59
	v_mov_b32_e32 v99, v61
	v_pk_add_f32 v[92:93], v[92:93], v[98:99]
	v_pk_add_f32 v[94:95], v[56:57], v[0:1]
	v_pk_add_f32 v[98:99], v[92:93], v[92:93] op_sel:[0,1] op_sel_hi:[1,0]
	global_load_dwordx4 v[90:93], v[90:91], off
	v_mov_b32_e32 v0, v55
	v_pk_add_f32 v[96:97], v[54:55], v[0:1]
	v_mov_b32_e32 v95, v53
	v_mov_b32_e32 v97, v52
	v_mov_b32_e32 v99, v51
	v_pk_add_f32 v[94:95], v[96:97], v[94:95]
	s_waitcnt vmcnt(0)
	v_mov_b32_e32 v100, v90
	v_mov_b32_e32 v101, v92
	v_mov_b32_e32 v106, v91
	v_mov_b32_e32 v107, v93
	v_pk_add_f32 v[100:101], v[100:101], v[106:107]
	s_nop 0
	v_add_f32_e32 v0, v100, v101
	v_add_f32_e32 v100, 0, v0
	v_mov_b32_e32 v101, v50
	v_pk_add_f32 v[96:97], v[100:101], v[98:99]
	s_nop 0
	v_pk_add_f32 v[94:95], v[96:97], v[94:95]
	s_nop 0
	v_add_f32_e32 v0, v94, v95
	ds_bpermute_b32 v94, v69, v0
	s_waitcnt lgkmcnt(0)
	v_add_f32_e32 v0, v0, v94
	ds_bpermute_b32 v94, v71, v0
	s_waitcnt lgkmcnt(0)
	v_add_f32_e32 v0, v0, v94
	ds_bpermute_b32 v94, v73, v0
	s_waitcnt lgkmcnt(0)
	v_add_f32_e32 v0, v0, v94
	ds_bpermute_b32 v94, v102, v0
	s_waitcnt lgkmcnt(0)
	v_add_f32_e32 v0, v0, v94
	ds_bpermute_b32 v94, v103, v0
	s_waitcnt lgkmcnt(0)
	v_add_f32_e32 v0, v0, v94
	ds_bpermute_b32 v94, v104, v0
	s_waitcnt lgkmcnt(0)
	v_add_f32_e32 v0, v0, v94
	v_mul_f32_e32 v0, 0x3a800000, v0
	v_pk_add_f32 v[96:97], v[90:91], v[0:1] op_sel_hi:[1,0] neg_lo:[0,1] neg_hi:[0,1]
	v_pk_add_f32 v[98:99], v[92:93], v[0:1] op_sel_hi:[1,0] neg_lo:[0,1] neg_hi:[0,1]
	v_mov_b32_e32 v92, v97
	v_mov_b32_e32 v93, v99
	v_mov_b32_e32 v90, v96
	v_mov_b32_e32 v91, v98
	v_pk_mul_f32 v[92:93], v[92:93], v[92:93]
	s_nop 0
	v_pk_fma_f32 v[90:91], v[90:91], v[90:91], v[92:93]
	v_pk_add_f32 v[92:93], v[58:59], v[0:1] op_sel_hi:[1,0] neg_lo:[0,1] neg_hi:[0,1]
	v_pk_add_f32 v[94:95], v[90:91], v[90:91] op_sel_hi:[0,1]
	v_pk_add_f32 v[90:91], v[60:61], v[0:1] op_sel_hi:[1,0] neg_lo:[0,1] neg_hi:[0,1]
	v_mov_b32_e32 v60, v93
	v_mov_b32_e32 v61, v91
	v_mov_b32_e32 v58, v92
	v_mov_b32_e32 v59, v90
	v_pk_mul_f32 v[60:61], v[60:61], v[60:61]
	s_nop 0
	v_pk_fma_f32 v[58:59], v[58:59], v[58:59], v[60:61]
	v_pk_add_f32 v[60:61], v[54:55], v[0:1] op_sel_hi:[1,0] neg_lo:[0,1] neg_hi:[0,1]
	v_pk_add_f32 v[100:101], v[58:59], v[58:59] op_sel_hi:[0,1]
	v_pk_add_f32 v[58:59], v[56:57], v[0:1] op_sel_hi:[1,0] neg_lo:[0,1] neg_hi:[0,1]
	v_mul_f32_e32 v54, v60, v60
	v_pk_fma_f32 v[106:107], v[60:61], v[60:61], v[54:55] op_sel_hi:[1,1,0]
	v_mul_f32_e32 v54, v58, v58
	v_pk_fma_f32 v[108:109], v[58:59], v[58:59], v[54:55] op_sel_hi:[1,1,0]
	v_pk_add_f32 v[56:57], v[50:51], v[0:1] op_sel_hi:[1,0] neg_lo:[0,1] neg_hi:[0,1]
	v_pk_add_f32 v[54:55], v[52:53], v[0:1] op_sel_hi:[1,0] neg_lo:[0,1] neg_hi:[0,1]
	v_pk_mul_f32 v[50:51], v[56:57], v[56:57]
	v_pk_mul_f32 v[52:53], v[54:55], v[54:55]
	v_mov_b32_e32 v106, v50
	v_mov_b32_e32 v108, v51
	v_mov_b32_e32 v94, v52
	v_mov_b32_e32 v100, v53
	v_pk_add_f32 v[50:51], v[106:107], v[108:109]
	v_pk_add_f32 v[52:53], v[94:95], v[100:101]
	s_nop 0
	v_pk_add_f32 v[50:51], v[50:51], v[52:53]
	s_nop 0
	v_add_f32_e32 v0, v50, v51
	ds_bpermute_b32 v50, v69, v0
	s_waitcnt lgkmcnt(0)
	v_add_f32_e32 v0, v0, v50
	ds_bpermute_b32 v50, v71, v0
	s_waitcnt lgkmcnt(0)
	v_add_f32_e32 v0, v0, v50
	ds_bpermute_b32 v50, v73, v0
	s_waitcnt lgkmcnt(0)
	v_add_f32_e32 v0, v0, v50
	ds_bpermute_b32 v50, v102, v0
	s_waitcnt lgkmcnt(0)
	v_add_f32_e32 v0, v0, v50
	ds_bpermute_b32 v50, v103, v0
	s_waitcnt lgkmcnt(0)
	v_add_f32_e32 v0, v0, v50
	ds_bpermute_b32 v50, v104, v0
	s_waitcnt lgkmcnt(0)
	v_add_f32_e32 v0, v0, v50
	v_mov_b32_e32 v50, 0x3727c5ac
	v_fmamk_f32 v0, v0, 0x3a800000, v50
	v_cmp_gt_f32_e32 vcc, s37, v0
	v_mul_f32_e32 v50, 0x4b800000, v0
	s_nop 0
	v_cndmask_b32_e32 v0, v0, v50, vcc
	v_rsq_f32_e32 v0, v0
	s_nop 0
	v_mul_f32_e32 v50, 0x45800000, v0
	v_cndmask_b32_e32 v94, v0, v50, vcc
	v_pk_mul_f32 v[50:51], v[96:97], v[94:95] op_sel_hi:[1,0]
	v_pk_mul_f32 v[52:53], v[98:99], v[94:95] op_sel_hi:[1,0]
	v_pk_fma_f32 v[50:51], v[2:3], v[50:51], v[10:11]
	v_pk_fma_f32 v[52:53], v[4:5], v[52:53], v[12:13]
	v_lshl_add_u64 v[96:97], v[82:83], 0, v[78:79]
	s_and_saveexec_b64 s[42:43], s[52:53]
	s_cbranch_execz .LBB0_34
	global_store_dwordx4 v[96:97], v[50:53], off sc1

; DI void phase_ln(const P& p, int l) {
;     ...
;       for (int i = 0; i < 4; ++i) {
;         const int col = i * 256 + lane * 4;
;         float4 y;
;         y.x = v[h][i].x * rstd * g4[i].x + b4[i].x;
;         y.y = v[h][i].y * rstd * g4[i].y + b4[i].y;
;         y.z = v[h][i].z * rstd * g4[i].z + b4[i].z;
;         y.w = v[h][i].w * rstd * g4[i].w + b4[i].w;
;         if (l == 1 || rr < MLAT) *(float4*)(p.out + (size_t)rr * 1024 + col) = y;
.LBB0_36:
	v_mov_b32_e32 v95, v94
	v_pk_mul_f32 v[50:51], v[92:93], v[94:95]
	v_pk_mul_f32 v[52:53], v[90:91], v[94:95]
	v_pk_fma_f32 v[50:51], v[6:7], v[50:51], v[14:15]
	v_pk_fma_f32 v[52:53], v[8:9], v[52:53], v[16:17]
	s_and_saveexec_b64 s[54:55], s[52:53]
	s_cbranch_execz .LBB0_38
	global_store_dwordx4 v[96:97], v[50:53], off offset:1024 sc1

; DI void phase_ln(const P& p, int l) {
;     ...
;       for (int i = 0; i < 4; ++i) {
;         const int col = i * 256 + lane * 4;
;         float4 y;
;         y.x = v[h][i].x * rstd * g4[i].x + b4[i].x;
;         y.y = v[h][i].y * rstd * g4[i].y + b4[i].y;
;         y.z = v[h][i].z * rstd * g4[i].z + b4[i].z;
;         y.w = v[h][i].w * rstd * g4[i].w + b4[i].w;
;         if (l == 1 || rr < MLAT) *(float4*)(p.out + (size_t)rr * 1024 + col) = y;
.LBB0_40:
	v_pk_mul_f32 v[50:51], v[60:61], v[94:95]
	v_pk_mul_f32 v[52:53], v[58:59], v[94:95]
	v_pk_fma_f32 v[50:51], v[18:19], v[50:51], v[26:27]
	v_pk_fma_f32 v[52:53], v[20:21], v[52:53], v[28:29]
	s_and_saveexec_b64 s[54:55], s[52:53]
	s_cbranch_execz .LBB0_42
	global_store_dwordx4 v[96:97], v[50:53], off offset:2048 sc1

; DI void phase_ln(const P& p, int l) {
;     ...
;       for (int i = 0; i < 4; ++i) {
;         const int col = i * 256 + lane * 4;
;         float4 y;
;         y.x = v[h][i].x * rstd * g4[i].x + b4[i].x;
;         y.y = v[h][i].y * rstd * g4[i].y + b4[i].y;
;         y.z = v[h][i].z * rstd * g4[i].z + b4[i].z;
;         y.w = v[h][i].w * rstd * g4[i].w + b4[i].w;
;         if (l == 1 || rr < MLAT) *(float4*)(p.out + (size_t)rr * 1024 + col) = y;
.LBB0_44:
	v_pk_mul_f32 v[50:51], v[56:57], v[94:95]
	v_pk_mul_f32 v[52:53], v[54:55], v[94:95]
	v_pk_fma_f32 v[50:51], v[22:23], v[50:51], v[30:31]
	v_pk_fma_f32 v[52:53], v[24:25], v[52:53], v[32:33]
	s_and_saveexec_b64 s[54:55], s[52:53]
	s_cbranch_execz .LBB0_47
	global_store_dwordx4 v[96:97], v[50:53], off offset:3072 sc1
	s_or_b64 exec, exec, s[54:55]
	s_and_b64 vcc, exec, s[42:43]
	s_cbranch_vccz .LBB0_48

; DI void phase_ln(const P& p, int l) {
;     ...
;     for (int h = 0; h < 2; ++h) {
;       if (h && !two) break;
;       const int rr = h ? rowb : row;
;       float s = 0.f;
; #pragma unroll
;       for (int i = 0; i < 4; ++i) s += (v[h][i].x + v[h][i].y) + (v[h][i].z + v[h][i].w);
; #pragma unroll
;       for (int o = 32; o >= 1; o >>= 1) s += __shfl_xor(s, o);
;       const float mean = s * (1.f / 1024.f);
;       float q = 0.f;
; #pragma unroll
;       for (int i = 0; i < 4; ++i) {
;         v[h][i].x -= mean; v[h][i].y -= mean; v[h][i].z -= mean; v[h][i].w -= mean;
;         q += (v[h][i].x * v[h][i].x + v[h][i].y * v[h][i].y) + (v[h][i].z * v[h][i].z + v[h][i].w * v[h][i].w);
;       }
; #pragma unroll
;       for (int o = 32; o >= 1; o >>= 1) q += __shfl_xor(q, o);
;       const float rstd = rsqrtf(q * (1.f / 1024.f) + 1e-5f);
;       const int mr = rr < MLAT ? (rr >> 11) : 16;
;       const float* md = p.mod + (size_t)(1 * 17 + mr) * 3072;
; #pragma unroll
;       for (int i = 0; i < 4; ++i) {
;         const int col = i * 256 + lane * 4;
;         float4 y;
;         y.x = v[h][i].x * rstd * g4[i].x + b4[i].x;
;         y.y = v[h][i].y * rstd * g4[i].y + b4[i].y;
;         y.z = v[h][i].z * rstd * g4[i].z + b4[i].z;
;         y.w = v[h][i].w * rstd * g4[i].w + b4[i].w;
;         if (l == 1 || rr < MLAT) *(float4*)(p.out + (size_t)rr * 1024 + col) = y;
.LBB0_49:
	v_mov_b32_e32 v50, v34
	v_mov_b32_e32 v51, v36
	v_mov_b32_e32 v52, v35
	v_mov_b32_e32 v53, v37
	v_pk_add_f32 v[50:51], v[50:51], v[52:53]
	v_mov_b32_e32 v52, v46
	v_mov_b32_e32 v53, v48
	v_mov_b32_e32 v54, v47
	v_mov_b32_e32 v55, v49
	v_pk_add_f32 v[52:53], v[52:53], v[54:55]
	v_mov_b32_e32 v54, v43
	v_mov_b32_e32 v56, v45
	v_add_f32_e32 v50, v50, v51
	v_pk_add_f32 v[52:53], v[52:53], v[52:53] op_sel:[0,1] op_sel_hi:[1,0]
	v_pk_add_f32 v[54:55], v[42:43], v[54:55]
	v_pk_add_f32 v[56:57], v[44:45], v[56:57]
	v_add_f32_e32 v50, 0, v50
	v_mov_b32_e32 v51, v38
	v_mov_b32_e32 v53, v39
	v_mov_b32_e32 v55, v40
	v_mov_b32_e32 v57, v41
	v_pk_add_f32 v[50:51], v[50:51], v[52:53]
	v_pk_add_f32 v[52:53], v[54:55], v[56:57]
	s_movk_i32 s2, 0x7fff
	v_pk_add_f32 v[50:51], v[50:51], v[52:53]
	v_cmp_gt_i32_e32 vcc, s2, v62
	v_add_f32_e32 v50, v50, v51
	ds_bpermute_b32 v51, v69, v50
	s_or_b64 s[40:41], s[46:47], vcc
	s_waitcnt lgkmcnt(0)
	v_add_f32_e32 v50, v50, v51
	ds_bpermute_b32 v51, v71, v50
	s_waitcnt lgkmcnt(0)
	v_add_f32_e32 v50, v50, v51
	ds_bpermute_b32 v51, v73, v50
	s_waitcnt lgkmcnt(0)
	v_add_f32_e32 v50, v50, v51
	ds_bpermute_b32 v51, v102, v50
	s_waitcnt lgkmcnt(0)
	v_add_f32_e32 v50, v50, v51
	ds_bpermute_b32 v51, v103, v50
	s_waitcnt lgkmcnt(0)
	v_add_f32_e32 v50, v50, v51
	ds_bpermute_b32 v51, v104, v50
	s_waitcnt lgkmcnt(0)
	v_add_f32_e32 v50, v50, v51
	v_mul_f32_e32 v52, 0x3a800000, v50
	v_pk_add_f32 v[50:51], v[46:47], v[52:53] op_sel_hi:[1,0] neg_lo:[0,1] neg_hi:[0,1]
	v_pk_add_f32 v[48:49], v[48:49], v[52:53] op_sel_hi:[1,0] neg_lo:[0,1] neg_hi:[0,1]
	v_mov_b32_e32 v54, v51
	v_mov_b32_e32 v55, v49
	v_mov_b32_e32 v46, v50
	v_mov_b32_e32 v47, v48
	v_pk_mul_f32 v[54:55], v[54:55], v[54:55]
	v_pk_add_f32 v[44:45], v[44:45], v[52:53] op_sel_hi:[1,0] neg_lo:[0,1] neg_hi:[0,1]
	v_pk_fma_f32 v[46:47], v[46:47], v[46:47], v[54:55]
	v_pk_add_f32 v[36:37], v[36:37], v[52:53] op_sel_hi:[1,0] neg_lo:[0,1] neg_hi:[0,1]
	v_pk_add_f32 v[54:55], v[46:47], v[46:47] op_sel_hi:[0,1]
	v_pk_add_f32 v[46:47], v[42:43], v[52:53] op_sel_hi:[1,0] neg_lo:[0,1] neg_hi:[0,1]
	v_pk_add_f32 v[34:35], v[34:35], v[52:53] op_sel_hi:[1,0] neg_lo:[0,1] neg_hi:[0,1]
	v_mul_f32_e32 v42, v46, v46
	v_pk_fma_f32 v[56:57], v[46:47], v[46:47], v[42:43] op_sel_hi:[1,1,0]
	v_mul_f32_e32 v42, v44, v44
	v_mov_b32_e32 v90, v35
	v_mov_b32_e32 v91, v37
	v_pk_fma_f32 v[58:59], v[44:45], v[44:45], v[42:43] op_sel_hi:[1,1,0]
	v_pk_add_f32 v[42:43], v[38:39], v[52:53] op_sel_hi:[1,0] neg_lo:[0,1] neg_hi:[0,1]
	v_pk_add_f32 v[38:39], v[40:41], v[52:53] op_sel_hi:[1,0] neg_lo:[0,1] neg_hi:[0,1]
	v_mov_b32_e32 v52, v34
	v_mov_b32_e32 v53, v36
	v_pk_mul_f32 v[90:91], v[90:91], v[90:91]
	v_pk_mul_f32 v[40:41], v[42:43], v[42:43]
	v_pk_fma_f32 v[52:53], v[52:53], v[52:53], v[90:91]
	v_pk_mul_f32 v[60:61], v[38:39], v[38:39]
	v_pk_add_f32 v[52:53], v[52:53], v[52:53] op_sel_hi:[0,1]
	v_mov_b32_e32 v56, v40
	v_mov_b32_e32 v58, v41
	v_mov_b32_e32 v52, v60
	v_mov_b32_e32 v54, v61
	v_pk_add_f32 v[40:41], v[56:57], v[58:59]
	v_pk_add_f32 v[52:53], v[52:53], v[54:55]
	s_nop 0
	v_pk_add_f32 v[40:41], v[40:41], v[52:53]
	v_lshl_add_u64 v[52:53], v[74:75], 0, v[88:89]
	v_add_f32_e32 v40, v40, v41
	ds_bpermute_b32 v41, v69, v40
	s_waitcnt lgkmcnt(0)
	v_add_f32_e32 v40, v40, v41
	ds_bpermute_b32 v41, v71, v40
	s_waitcnt lgkmcnt(0)
	v_add_f32_e32 v40, v40, v41
	ds_bpermute_b32 v41, v73, v40
	s_waitcnt lgkmcnt(0)
	v_add_f32_e32 v40, v40, v41
	ds_bpermute_b32 v41, v102, v40
	s_waitcnt lgkmcnt(0)
	v_add_f32_e32 v40, v40, v41
	ds_bpermute_b32 v41, v103, v40
	s_waitcnt lgkmcnt(0)
	v_add_f32_e32 v40, v40, v41
	ds_bpermute_b32 v41, v104, v40
	s_waitcnt lgkmcnt(0)
	v_add_f32_e32 v40, v40, v41
	v_mov_b32_e32 v41, 0x3727c5ac
	v_fmamk_f32 v40, v40, 0x3a800000, v41
	v_cmp_gt_f32_e32 vcc, s37, v40
	v_mul_f32_e32 v41, 0x4b800000, v40
	s_nop 0
	v_cndmask_b32_e32 v40, v40, v41, vcc
	v_rsq_f32_e32 v40, v40
	s_nop 0
	v_mul_f32_e32 v41, 0x45800000, v40
	v_cndmask_b32_e32 v40, v40, v41, vcc
	v_pk_mul_f32 v[34:35], v[34:35], v[40:41] op_sel_hi:[1,0]
	v_pk_mul_f32 v[36:37], v[36:37], v[40:41] op_sel_hi:[1,0]
	v_pk_fma_f32 v[34:35], v[2:3], v[34:35], v[10:11]
	v_pk_fma_f32 v[36:37], v[4:5], v[36:37], v[12:13]
	s_and_saveexec_b64 s[54:55], s[40:41]
	s_cbranch_execz .LBB0_51
	global_store_dwordx4 v[52:53], v[34:37], off sc1

; DI void phase_ln(const P& p, int l) {
;     ...
;       for (int i = 0; i < 4; ++i) {
;         const int col = i * 256 + lane * 4;
;         float4 y;
;         y.x = v[h][i].x * rstd * g4[i].x + b4[i].x;
;         y.y = v[h][i].y * rstd * g4[i].y + b4[i].y;
;         y.z = v[h][i].z * rstd * g4[i].z + b4[i].z;
;         y.w = v[h][i].w * rstd * g4[i].w + b4[i].w;
;         if (l == 1 || rr < MLAT) *(float4*)(p.out + (size_t)rr * 1024 + col) = y;
.LBB0_53:
	v_mov_b32_e32 v41, v40
	v_pk_mul_f32 v[34:35], v[50:51], v[40:41]
	v_pk_mul_f32 v[36:37], v[48:49], v[40:41]
	v_pk_fma_f32 v[34:35], v[6:7], v[34:35], v[14:15]
	v_pk_fma_f32 v[36:37], v[8:9], v[36:37], v[16:17]
	s_and_saveexec_b64 s[54:55], s[40:41]
	s_cbranch_execz .LBB0_55
	global_store_dwordx4 v[52:53], v[34:37], off offset:1024 sc1

; DI void phase_ln(const P& p, int l) {
;     ...
;       for (int i = 0; i < 4; ++i) {
;         const int col = i * 256 + lane * 4;
;         float4 y;
;         y.x = v[h][i].x * rstd * g4[i].x + b4[i].x;
;         y.y = v[h][i].y * rstd * g4[i].y + b4[i].y;
;         y.z = v[h][i].z * rstd * g4[i].z + b4[i].z;
;         y.w = v[h][i].w * rstd * g4[i].w + b4[i].w;
;         if (l == 1 || rr < MLAT) *(float4*)(p.out + (size_t)rr * 1024 + col) = y;
.LBB0_57:
	v_pk_mul_f32 v[34:35], v[46:47], v[40:41]
	v_pk_mul_f32 v[36:37], v[44:45], v[40:41]
	v_pk_fma_f32 v[34:35], v[18:19], v[34:35], v[26:27]
	v_pk_fma_f32 v[36:37], v[20:21], v[36:37], v[28:29]
	s_and_saveexec_b64 s[54:55], s[40:41]
	s_cbranch_execz .LBB0_59
	global_store_dwordx4 v[52:53], v[34:37], off offset:2048 sc1

; DI void phase_ln(const P& p, int l) {
;     ...
;       for (int i = 0; i < 4; ++i) {
;         const int col = i * 256 + lane * 4;
;         float4 y;
;         y.x = v[h][i].x * rstd * g4[i].x + b4[i].x;
;         y.y = v[h][i].y * rstd * g4[i].y + b4[i].y;
;         y.z = v[h][i].z * rstd * g4[i].z + b4[i].z;
;         y.w = v[h][i].w * rstd * g4[i].w + b4[i].w;
;         if (l == 1 || rr < MLAT) *(float4*)(p.out + (size_t)rr * 1024 + col) = y;
.LBB0_61:
	v_pk_mul_f32 v[34:35], v[42:43], v[40:41]
	v_pk_mul_f32 v[36:37], v[38:39], v[40:41]
	v_pk_fma_f32 v[34:35], v[22:23], v[34:35], v[30:31]
	v_pk_fma_f32 v[36:37], v[24:25], v[36:37], v[32:33]
	s_and_saveexec_b64 s[54:55], s[40:41]
	s_cbranch_execz .LBB0_63
	global_store_dwordx4 v[52:53], v[34:37], off offset:3072 sc1

; DI int tidx() { int t = threadIdx.x; asm volatile("" : "+v"(t)); return t; }
; DI void transpose_item(const float* __restrict__ W, u16* __restrict__ Wt, int N, int kt, int nt2, char* lds) {
;   const int tid512 = tidx();
;   const int hb = tid512 >> 8, tid = tid512 & 255, nt = nt2 * 2 + hb;
;   u16* tile = (u16*)lds + hb * (64 * 72);
;   {
;     const int r = tid >> 2, cs = (tid & 3) * 16;
;     const float* src = W + (size_t)(kt * 64 + r) * N + nt * 64 + cs;
;     float4 v[4];
; #pragma unroll
;     for (int q = 0; q < 4; ++q) v[q] = *(const float4*)(src + q * 4);
; #pragma unroll
;     for (int q = 0; q < 4; ++q) {
;       const unsigned u01 = pack2(v[q].x, v[q].y), u23 = pack2(v[q].z, v[q].w);
;       tile[(cs + q * 4 + 0) * 72 + r] = (u16)u01;
;       tile[(cs + q * 4 + 1) * 72 + r] = (u16)(u01 >> 16);
;       tile[(cs + q * 4 + 2) * 72 + r] = (u16)u23;
;       tile[(cs + q * 4 + 3) * 72 + r] = (u16)(u23 >> 16);
;     }
;   }
;   __syncthreads();
;   {
;     const int n = tid >> 2, ks = (tid & 3) * 16;
;     uint4 a = *(const uint4*)&tile[n * 72 + ks];
;     uint4 b = *(const uint4*)&tile[n * 72 + ks + 8];
;     u16* dst = Wt + (size_t)(nt * 64 + n) * 1024 + kt * 64 + ks;
;     *(uint4*)dst = a;
;     *(uint4*)(dst + 8) = b;
;   }
;   __syncthreads();
; }
; DI void phase_prep(const P& p, char* lds) {
;   for (int it = blockIdx.x; it < 192 + 960 + 256; it += gridDim.x) {
;     if (it < 192) {
;       mod_item(p, it, lds);
;     } else if (it < 192 + 960) {
;       int t = it - 192;
;       int l = t / 480, rem = t % 480;
;       int kt = rem / 30, nt2 = rem % 30;
;       transpose_item(p.w_in + (size_t)l * 1024 * NIN, p.Wt + (size_t)l * NIN * 1024, NIN, kt, nt2, lds);
;     } else {
;       int t = it - 192 - 960;
;       int l = t >> 7, rem = t & 127;
;       int kt = rem >> 3, nt2 = rem & 7;
;       transpose_item(p.w_out + (size_t)l * 1024 * 1024, p.Wot + (size_t)l * 1024 * 1024, 1024, kt, nt2, lds);
.LBB0_961:
	s_cmpk_gt_i32 s23, 0xbf
	s_mov_b64 s[0:1], -1
	s_cbranch_scc0 .LBB0_967
	s_cmpk_gt_u32 s23, 0x47f
	s_cbranch_scc0 .LBB0_964
	s_add_i32 s0, s23, 0xfffffb80
	s_lshr_b32 s2, s0, 7
	v_readlane_b32 s52, v255, 5
	s_lshl_b64 s[0:1], s[2:3], 22
	v_readlane_b32 s62, v255, 15
	v_readlane_b32 s63, v255, 16
	s_add_u32 s24, s62, s0
	s_addc_u32 s25, s63, s1
	s_lshl_b64 s[0:1], s[2:3], 21
	s_add_u32 s0, s14, s0
	v_mov_b32_e32 v0, v195
	s_addc_u32 s1, s15, s1
	s_lshl_b32 s2, s23, 3
	v_ashrrev_i32_e32 v20, 8, v0
	v_bfe_u32 v21, v0, 2, 6
	v_lshlrev_b32_e32 v0, 4, v0
	s_and_b32 s2, s2, 0x3c0
	v_and_b32_e32 v22, 48, v0
	v_or_b32_e32 v0, s2, v21
	v_lshlrev_b32_e32 v0, 12, v0
	v_lshl_add_u64 v[2:3], s[24:25], 0, v[0:1]
	s_lshl_b32 s24, s23, 7
	s_and_b32 s24, s24, 0x380
	v_lshl_add_u32 v18, v20, 6, s24
	v_ashrrev_i32_e32 v19, 31, v18
	v_lshl_add_u64 v[2:3], v[18:19], 2, v[2:3]
	v_lshlrev_b32_e32 v0, 2, v22
	v_lshl_add_u64 v[14:15], v[2:3], 0, v[0:1]
	global_load_dwordx4 v[2:5], v[14:15], off
	global_load_dwordx4 v[6:9], v[14:15], off offset:16
	global_load_dwordx4 v[10:13], v[14:15], off offset:32
	s_nop 0
	global_load_dwordx4 v[14:17], v[14:15], off offset:48
	s_movk_i32 s24, 0x2400
	v_mul_u32_u24_e32 v19, 0x48, v22
	v_mad_i32_i24 v20, v20, s24, 32
	v_lshlrev_b32_e32 v0, 1, v21
	v_lshlrev_b32_e32 v19, 1, v19
	v_mul_u32_u24_e32 v23, 0x90, v21
	v_add3_u32 v24, v20, v0, v19
	v_add3_u32 v25, v20, v19, v0
	v_lshlrev_b32_e32 v0, 1, v22
	v_or_b32_e32 v18, v18, v21
	v_add3_u32 v20, v20, v23, v0
	v_ashrrev_i32_e32 v19, 31, v18
	v_lshlrev_b64 v[18:19], 11, v[18:19]
	s_lshl_b32 s2, s2, 1
	v_readlane_b32 s53, v255, 6
	v_readlane_b32 s54, v255, 7
	v_readlane_b32 s55, v255, 8
	v_readlane_b32 s56, v255, 9
	v_readlane_b32 s57, v255, 10
	v_readlane_b32 s58, v255, 11
	v_readlane_b32 s59, v255, 12
	v_readlane_b32 s60, v255, 13
	v_readlane_b32 s61, v255, 14
	v_readlane_b32 s64, v255, 17
	v_readlane_b32 s65, v255, 18
	v_readlane_b32 s66, v255, 19
	v_readlane_b32 s67, v255, 20
	s_waitcnt vmcnt(3)
	v_cvt_pk_bf16_f32 v2, v2, v3
	v_cvt_pk_bf16_f32 v3, v4, v5
	s_waitcnt vmcnt(2)
	v_cvt_pk_bf16_f32 v4, v6, v7
	v_cvt_pk_bf16_f32 v5, v8, v9
	s_waitcnt vmcnt(1)
	v_cvt_pk_bf16_f32 v6, v10, v11
	v_cvt_pk_bf16_f32 v7, v12, v13
	s_waitcnt vmcnt(0)
	v_cvt_pk_bf16_f32 v8, v14, v15
	v_cvt_pk_bf16_f32 v9, v16, v17
	ds_write_b16 v24, v2
	ds_write_b16_d16_hi v25, v2 offset:144
	ds_write_b16 v25, v3 offset:288
	ds_write_b16_d16_hi v25, v3 offset:432
	ds_write_b16 v24, v4 offset:576
	ds_write_b16_d16_hi v25, v4 offset:720
	ds_write_b16 v25, v5 offset:864
	ds_write_b16_d16_hi v25, v5 offset:1008
	ds_write_b16 v24, v6 offset:1152
	ds_write_b16_d16_hi v25, v6 offset:1296
	ds_write_b16 v25, v7 offset:1440
	ds_write_b16_d16_hi v25, v7 offset:1584
	ds_write_b16 v24, v8 offset:1728
	ds_write_b16_d16_hi v25, v8 offset:1872
	ds_write_b16 v25, v9 offset:2016
	ds_write_b16_d16_hi v25, v9 offset:2160
	s_waitcnt lgkmcnt(0)
	s_barrier
	ds_read_b128 v[2:5], v20
	ds_read_b128 v[6:9], v20 offset:16
	v_lshl_add_u64 v[10:11], s[0:1], 0, v[18:19]
	v_lshl_add_u64 v[10:11], v[10:11], 0, s[2:3]
	v_lshl_add_u64 v[10:11], v[10:11], 0, v[0:1]
	s_waitcnt lgkmcnt(1)
	global_store_dwordx4 v[10:11], v[2:5], off sc1
	s_waitcnt lgkmcnt(0)
	global_store_dwordx4 v[10:11], v[6:9], off offset:16 sc1
	s_barrier
	s_mov_b64 s[0:1], 0
.LBB0_964:
	s_andn2_b64 vcc, exec, s[0:1]
	s_cbranch_vccnz .LBB0_966
	s_add_i32 s0, s23, 0xffffff40
	s_add_i32 s1, s23, 0xfffffd60
	s_cmpk_lt_u32 s0, 0x1e0
	s_cselect_b32 s1, s0, s1
	s_mul_hi_u32 s2, s1, 0x88888889
	s_lshr_b32 s2, s2, 4
	s_mul_i32 s24, s2, 30
	s_sub_i32 s26, s1, s24
	s_cmpk_gt_u32 s0, 0x1df
	v_readlane_b32 s52, v255, 5
	v_mov_b32_e32 v0, v195
	s_cselect_b32 s0, 0xf00000, 0
	v_readlane_b32 s60, v255, 13
	s_cselect_b32 s1, 0x780000, 0
	v_readlane_b32 s61, v255, 14
	s_add_u32 s24, s60, s0
	v_ashrrev_i32_e32 v20, 8, v0
	v_bfe_u32 v21, v0, 2, 6
	v_lshlrev_b32_e32 v0, 4, v0
	s_addc_u32 s25, s61, 0
	v_and_b32_e32 v22, 48, v0
	v_lshl_or_b32 v0, s2, 6, v21
	s_movk_i32 s27, 0xf00
	s_add_u32 s0, s12, s1
	v_mul_lo_u32 v0, v0, s27
	s_addc_u32 s1, s13, 0
	v_lshl_add_u64 v[2:3], v[0:1], 2, s[24:25]
	s_lshl_b32 s24, s26, 7
	v_lshl_add_u32 v18, v20, 6, s24
	v_ashrrev_i32_e32 v19, 31, v18
	v_lshl_add_u64 v[2:3], v[18:19], 2, v[2:3]
	v_lshlrev_b32_e32 v0, 2, v22
	v_lshl_add_u64 v[14:15], v[2:3], 0, v[0:1]
	global_load_dwordx4 v[2:5], v[14:15], off
	global_load_dwordx4 v[6:9], v[14:15], off offset:16
	global_load_dwordx4 v[10:13], v[14:15], off offset:32
	s_nop 0
	global_load_dwordx4 v[14:17], v[14:15], off offset:48
	s_movk_i32 s24, 0x2400
	v_mul_u32_u24_e32 v19, 0x48, v22
	v_mad_i32_i24 v20, v20, s24, 32
	v_lshlrev_b32_e32 v0, 1, v21
	v_lshlrev_b32_e32 v19, 1, v19
	v_mul_u32_u24_e32 v23, 0x90, v21
	v_add3_u32 v24, v20, v0, v19
	v_add3_u32 v25, v20, v19, v0
	v_lshlrev_b32_e32 v0, 1, v22
	v_or_b32_e32 v18, v18, v21
	v_add3_u32 v20, v20, v23, v0
	v_ashrrev_i32_e32 v19, 31, v18
	v_lshlrev_b64 v[18:19], 11, v[18:19]
	s_lshl_b32 s2, s2, 7
	v_readlane_b32 s53, v255, 6
	v_readlane_b32 s54, v255, 7
	v_readlane_b32 s55, v255, 8
	v_readlane_b32 s56, v255, 9
	v_readlane_b32 s57, v255, 10
	v_readlane_b32 s58, v255, 11
	v_readlane_b32 s59, v255, 12
	v_readlane_b32 s62, v255, 15
	v_readlane_b32 s63, v255, 16
	v_readlane_b32 s64, v255, 17
	v_readlane_b32 s65, v255, 18
	v_readlane_b32 s66, v255, 19
	v_readlane_b32 s67, v255, 20
	s_waitcnt vmcnt(3)
	v_cvt_pk_bf16_f32 v2, v2, v3
	v_cvt_pk_bf16_f32 v3, v4, v5
	s_waitcnt vmcnt(2)
	v_cvt_pk_bf16_f32 v4, v6, v7
	v_cvt_pk_bf16_f32 v5, v8, v9
	s_waitcnt vmcnt(1)
	v_cvt_pk_bf16_f32 v6, v10, v11
	v_cvt_pk_bf16_f32 v7, v12, v13
	s_waitcnt vmcnt(0)
	v_cvt_pk_bf16_f32 v8, v14, v15
	v_cvt_pk_bf16_f32 v9, v16, v17
	ds_write_b16 v24, v2
	ds_write_b16_d16_hi v25, v2 offset:144
	ds_write_b16 v25, v3 offset:288
	ds_write_b16_d16_hi v25, v3 offset:432
	ds_write_b16 v24, v4 offset:576
	ds_write_b16_d16_hi v25, v4 offset:720
	ds_write_b16 v25, v5 offset:864
	ds_write_b16_d16_hi v25, v5 offset:1008
	ds_write_b16 v24, v6 offset:1152
	ds_write_b16_d16_hi v25, v6 offset:1296
	ds_write_b16 v25, v7 offset:1440
	ds_write_b16_d16_hi v25, v7 offset:1584
	ds_write_b16 v24, v8 offset:1728
	ds_write_b16_d16_hi v25, v8 offset:1872
	ds_write_b16 v25, v9 offset:2016
	ds_write_b16_d16_hi v25, v9 offset:2160
	s_waitcnt lgkmcnt(0)
	s_barrier
	ds_read_b128 v[2:5], v20
	ds_read_b128 v[6:9], v20 offset:16
	v_lshl_add_u64 v[10:11], s[0:1], 0, v[18:19]
	v_lshl_add_u64 v[10:11], v[10:11], 0, s[2:3]
	v_lshl_add_u64 v[10:11], v[10:11], 0, v[0:1]
	s_waitcnt lgkmcnt(1)
	global_store_dwordx4 v[10:11], v[2:5], off sc1
	s_waitcnt lgkmcnt(0)
	global_store_dwordx4 v[10:11], v[6:9], off offset:16 sc1
	s_barrier
